# v29: v22 + unmasked attention tiles software-pipelined: exp of key block a under the QK MFMAs of block b, 16-key softmax slices under the k-outer P.V MFMAs; tile max still tested before accumulation,
# speedup vs baseline: 1.0076x; 1.0045x over previous
; template <int PM> DI void attn_phase(const Params& p, int l, char* smem, int* s_item, int wv, int cidx) {
;     ...
;       for (int i = 0; i < ntl; ++i) {
;         const int cur = i & 1;
;         const int vprev = vcur ^ 1, vnext = vcur ^ 1;
;         const bool more = (i + 1 < ntl);
;         if (PM != 2 && more) {
; #pragma unroll
;           for (int j = 0; j < 2; ++j) {
;             *(u32x4*)(Kb0 + (cur ^ 1) * 17408 + (trow + 32 * j) * 272 + tch * 16) = kst[j];
;             *(u32x4*)(Vb0 + vnext * 20480 + (trow + 32 * j) * 320 + tch * 16) = vst[j];
;           }
;         }
.LBB0_422:
	s_and_b32 s89, s2, 1
	s_cmp_eq_u32 s2, 0
	s_cselect_b32 s32, 1, 0
	s_xor_b32 s93, s95, 1
	s_add_i32 s94, s2, 1
	s_cmp_ge_i32 s94, s81
	s_cbranch_scc1 .LBB0_424
	s_xor_b32 s0, s89, 1
	s_mulk_i32 s0, 0x4400
	v_or_b32_e32 v0, s0, v196
	s_mul_i32 s0, s93, 0x5000
	v_or_b32_e32 v2, s0, v196
	v_add_u32_e32 v0, v0, v246
	v_add_u32_e32 v2, v2, v247
	s_waitcnt vmcnt(3)
	ds_write_b128 v0, v[180:183]
	s_waitcnt vmcnt(2)
	ds_write_b128 v2, v[184:187] offset:34816
	s_waitcnt vmcnt(1)
	ds_write_b128 v0, v[188:191] offset:8704
	s_waitcnt vmcnt(0)
	ds_write_b128 v2, v[192:195] offset:45056

; DI f32x16 mfma32(bf16x8 a, bf16x8 b, f32x16 c) { return __builtin_amdgcn_mfma_f32_32x32x16_bf16(a, b, c, 0, 0, 0); }
; template <int PM> DI void attn_phase(const Params& p, int l, char* smem, int* s_item, int wv, int cidx) {
;     ...
;         if (active) {
; #pragma unroll
;           for (int kb = 0; kb < 2; ++kb)
; #pragma unroll
;             for (int e = 0; e < 16; ++e) sacc[kb][e] = 0.f;
;           const char* Kc = Kb0 + cur * 17408 + l31 * 272 + dofs_b + h * 16;
;           bf16x8 kf[8];
;           if (full_d) {
; #pragma unroll
;             for (int j = 0; j < 8; ++j) kf[j] = *(const bf16x8*)(Kc + (j >> 3) * 32 * 272 + (j & 7) * 32);
; #pragma unroll
;             for (int j = 0; j < 16; ++j) {
;               sacc[j >> 3] = mfma32(kf[j & 7], qf[j & 7], sacc[j >> 3]);
;               if (j + 8 < 16) kf[j & 7] = *(const bf16x8*)(Kc + ((j + 8) >> 3) * 32 * 272 + ((j + 8) & 7) * 32);
;               __builtin_amdgcn_sched_barrier(0);
;             }
;           } else {
; #pragma unroll
;             for (int j = 0; j < 4; ++j) kf[j] = *(const bf16x8*)(Kc + (j >> 2) * 32 * 272 + (j & 3) * 32);
; #pragma unroll
;             for (int j = 0; j < 8; ++j) {
;               sacc[j >> 2] = mfma32(kf[j & 3], qf[j & 3], sacc[j >> 2]);
;               if (j + 4 < 8) kf[j & 3] = *(const bf16x8*)(Kc + ((j + 4) >> 2) * 32 * 272 + ((j + 4) & 3) * 32);
;               __builtin_amdgcn_sched_barrier(0);
;             }
;           }
.Lfa_redo:
	v_add_u32_e32 v0, s89, v234
	ds_read_b128 v[48:51], v0
	ds_read_b128 v[10:13], v0 offset:32
	ds_read_b128 v[6:9], v0 offset:64
	ds_read_b128 v[2:5], v0 offset:96
	s_cmp_lg_u64 s[0:1], 0
	s_cbranch_scc1 .Lfa_orig
	s_cmp_eq_u32 s32, 0
	s_cbranch_scc1 .Lfa_fast
.Lfa_orig:
	s_and_b64 vcc, exec, s[72:73]
	s_mov_b64 s[2:3], -1
	s_cbranch_vccnz .LBB0_438
	ds_read_b128 v[32:35], v0 offset:128
	ds_read_b128 v[36:39], v0 offset:160
	ds_read_b128 v[40:43], v0 offset:192
	ds_read_b128 v[44:47], v0 offset:224
	ds_read_b128 v[52:55], v0 offset:8704
	s_waitcnt lgkmcnt(8)
	v_mfma_f32_32x32x16_bf16 v[16:31], v[48:51], v[148:151], 0
	s_waitcnt lgkmcnt(7)
	v_mfma_f32_32x32x16_bf16 v[16:31], v[10:13], v[152:155], v[16:31]
	ds_read_b128 v[56:59], v0 offset:8736
	s_waitcnt lgkmcnt(7)
	v_mfma_f32_32x32x16_bf16 v[16:31], v[6:9], v[156:159], v[16:31]
	ds_read_b128 v[60:63], v0 offset:8768
	s_waitcnt lgkmcnt(7)
	v_mfma_f32_32x32x16_bf16 v[16:31], v[2:5], v[160:163], v[16:31]
	ds_read_b128 v[64:67], v0 offset:8800
	s_waitcnt lgkmcnt(7)
	v_mfma_f32_32x32x16_bf16 v[16:31], v[32:35], v[164:167], v[16:31]
	ds_read_b128 v[68:71], v0 offset:8832
	s_waitcnt lgkmcnt(7)
	v_mfma_f32_32x32x16_bf16 v[16:31], v[36:39], v[168:171], v[16:31]
	ds_read_b128 v[72:75], v0 offset:8864
	s_waitcnt lgkmcnt(7)
	v_mfma_f32_32x32x16_bf16 v[16:31], v[40:43], v[172:175], v[16:31]
	ds_read_b128 v[76:79], v0 offset:8896
	s_waitcnt lgkmcnt(7)
	v_mfma_f32_32x32x16_bf16 v[16:31], v[44:47], v[176:179], v[16:31]
	ds_read_b128 v[144:147], v0 offset:8928
	s_waitcnt lgkmcnt(7)
	v_mfma_f32_32x32x16_bf16 v[32:47], v[52:55], v[148:151], 0
	s_waitcnt lgkmcnt(6)
	v_mfma_f32_32x32x16_bf16 v[32:47], v[56:59], v[152:155], v[32:47]
	s_waitcnt lgkmcnt(5)
	v_mfma_f32_32x32x16_bf16 v[32:47], v[60:63], v[156:159], v[32:47]
	s_waitcnt lgkmcnt(4)
	v_mfma_f32_32x32x16_bf16 v[32:47], v[64:67], v[160:163], v[32:47]
	s_waitcnt lgkmcnt(3)
	v_mfma_f32_32x32x16_bf16 v[32:47], v[68:71], v[164:167], v[32:47]
	s_waitcnt lgkmcnt(2)
	v_mfma_f32_32x32x16_bf16 v[32:47], v[72:75], v[168:171], v[32:47]
	s_waitcnt lgkmcnt(1)
	v_mfma_f32_32x32x16_bf16 v[32:47], v[76:79], v[172:175], v[32:47]
	s_waitcnt lgkmcnt(0)
	v_mfma_f32_32x32x16_bf16 v[32:47], v[144:147], v[176:179], v[32:47]
	s_mov_b64 s[2:3], 0

; DI float fexp2(float x) { return __builtin_amdgcn_exp2f(x); }
; DI f32x16 mfma32(bf16x8 a, bf16x8 b, f32x16 c) { return __builtin_amdgcn_mfma_f32_32x32x16_bf16(a, b, c, 0, 0, 0); }
; template <int PM> DI void attn_phase(const Params& p, int l, char* smem, int* s_item, int wv, int cidx) {
;     ...
;         if (active) {
; #pragma unroll
;           for (int kb = 0; kb < 2; ++kb)
; #pragma unroll
;             for (int e = 0; e < 16; ++e) sacc[kb][e] = 0.f;
;           const char* Kc = Kb0 + cur * 17408 + l31 * 272 + dofs_b + h * 16;
;           bf16x8 kf[8];
;           if (full_d) {
; #pragma unroll
;             for (int j = 0; j < 8; ++j) kf[j] = *(const bf16x8*)(Kc + (j >> 3) * 32 * 272 + (j & 7) * 32);
; #pragma unroll
;             for (int j = 0; j < 16; ++j) {
;               sacc[j >> 3] = mfma32(kf[j & 7], qf[j & 7], sacc[j >> 3]);
;               if (j + 8 < 16) kf[j & 7] = *(const bf16x8*)(Kc + ((j + 8) >> 3) * 32 * 272 + ((j + 8) & 7) * 32);
;               __builtin_amdgcn_sched_barrier(0);
;             }
;           } else {
; #pragma unroll
;             for (int j = 0; j < 4; ++j) kf[j] = *(const bf16x8*)(Kc + (j >> 2) * 32 * 272 + (j & 3) * 32);
; #pragma unroll
;             for (int j = 0; j < 8; ++j) {
;               sacc[j >> 2] = mfma32(kf[j & 3], qf[j & 3], sacc[j >> 2]);
;               if (j + 4 < 8) kf[j & 3] = *(const bf16x8*)(Kc + ((j + 4) >> 2) * 32 * 272 + ((j + 4) & 3) * 32);
;               __builtin_amdgcn_sched_barrier(0);
;             }
;           }
;     ...
;           float mt = sacc[0][0];
; #pragma unroll
;           for (int e = 1; e < 16; ++e) mt = fmaxf(mt, sacc[0][e]);
; #pragma unroll
;           for (int e = 0; e < 16; ++e) mt = fmaxf(mt, sacc[1][e]);
;           mt = half_max(mt);
;           if (__builtin_amdgcn_ballot_w64(mt > m + 8.f) != 0ull) {
;             const float mnew = fmaxf(m, mt);
;             const float alpha = fexp2(m - mnew);
;             m = mnew;
;             lsum *= alpha;
; #pragma unroll
;             for (int db = 0; db < 4; ++db)
; #pragma unroll
;               for (int e = 0; e < 16; ++e) Oacc[db][e] *= alpha;
;           }
;           float ps = 0.f;
; #pragma unroll
;           for (int kb = 0; kb < 2; ++kb)
; #pragma unroll
;             for (int e = 0; e < 16; ++e) { const float pv = fexp2(sacc[kb][e] - m); sacc[kb][e] = pv; ps += pv; }
;           lsum += ps;
.Lfa_fast:
	s_and_b64 vcc, exec, s[72:73]
	s_cbranch_vccnz .Lfa_half
	ds_read_b128 v[32:35], v0 offset:128
	ds_read_b128 v[36:39], v0 offset:160
	ds_read_b128 v[40:43], v0 offset:192
	ds_read_b128 v[44:47], v0 offset:224
	ds_read_b128 v[52:55], v0 offset:8704
	s_waitcnt lgkmcnt(8)
	v_mfma_f32_32x32x16_bf16 v[16:31], v[48:51], v[148:151], 0
	s_waitcnt lgkmcnt(7)
	v_mfma_f32_32x32x16_bf16 v[16:31], v[10:13], v[152:155], v[16:31]
	ds_read_b128 v[56:59], v0 offset:8736
	s_waitcnt lgkmcnt(7)
	v_mfma_f32_32x32x16_bf16 v[16:31], v[6:9], v[156:159], v[16:31]
	ds_read_b128 v[60:63], v0 offset:8768
	s_waitcnt lgkmcnt(7)
	v_mfma_f32_32x32x16_bf16 v[16:31], v[2:5], v[160:163], v[16:31]
	ds_read_b128 v[64:67], v0 offset:8800
	s_waitcnt lgkmcnt(7)
	v_mfma_f32_32x32x16_bf16 v[16:31], v[32:35], v[164:167], v[16:31]
	ds_read_b128 v[68:71], v0 offset:8832
	s_waitcnt lgkmcnt(7)
	v_mfma_f32_32x32x16_bf16 v[16:31], v[36:39], v[168:171], v[16:31]
	ds_read_b128 v[72:75], v0 offset:8864
	s_waitcnt lgkmcnt(7)
	v_mfma_f32_32x32x16_bf16 v[16:31], v[40:43], v[172:175], v[16:31]
	ds_read_b128 v[76:79], v0 offset:8896
	s_waitcnt lgkmcnt(7)
	v_mfma_f32_32x32x16_bf16 v[16:31], v[44:47], v[176:179], v[16:31]
	ds_read_b128 v[144:147], v0 offset:8928
	s_waitcnt lgkmcnt(7)
	v_mfma_f32_32x32x16_bf16 v[32:47], v[52:55], v[148:151], 0
	s_waitcnt lgkmcnt(6)
	v_mfma_f32_32x32x16_bf16 v[32:47], v[56:59], v[152:155], v[32:47]
	v_max3_f32 v0, v16, v17, v18
	v_max3_f32 v0, v0, v19, v20
	v_max3_f32 v0, v0, v21, v22
	v_max3_f32 v0, v0, v23, v24
	v_max3_f32 v0, v0, v25, v26
	s_waitcnt lgkmcnt(5)
	v_mfma_f32_32x32x16_bf16 v[32:47], v[60:63], v[156:159], v[32:47]
	v_max3_f32 v0, v0, v27, v28
	v_max3_f32 v0, v0, v29, v30
	v_max_f32_e32 v0, v0, v31
	v_sub_f32_e32 v10, v16, v233
	v_exp_f32_e32 v16, v10
	s_waitcnt lgkmcnt(4)
	v_mfma_f32_32x32x16_bf16 v[32:47], v[64:67], v[160:163], v[32:47]
	v_sub_f32_e32 v10, v17, v233
	v_exp_f32_e32 v17, v10
	v_sub_f32_e32 v10, v18, v233
	v_exp_f32_e32 v18, v10
	v_add_f32_e32 v15, 0, v16
	s_waitcnt lgkmcnt(3)
	v_mfma_f32_32x32x16_bf16 v[32:47], v[68:71], v[164:167], v[32:47]
	v_sub_f32_e32 v10, v19, v233
	v_exp_f32_e32 v19, v10
	v_add_f32_e32 v15, v17, v15
	v_sub_f32_e32 v10, v20, v233
	v_exp_f32_e32 v20, v10
	s_waitcnt lgkmcnt(2)
	v_mfma_f32_32x32x16_bf16 v[32:47], v[72:75], v[168:171], v[32:47]
	v_add_f32_e32 v15, v18, v15
	v_sub_f32_e32 v10, v21, v233
	v_exp_f32_e32 v21, v10
	v_add_f32_e32 v15, v19, v15
	v_sub_f32_e32 v10, v22, v233
	s_waitcnt lgkmcnt(1)
	v_mfma_f32_32x32x16_bf16 v[32:47], v[76:79], v[172:175], v[32:47]
	v_exp_f32_e32 v22, v10
	v_add_f32_e32 v15, v20, v15
	v_sub_f32_e32 v10, v23, v233
	v_exp_f32_e32 v23, v10
	v_add_f32_e32 v15, v21, v15
	s_waitcnt lgkmcnt(0)
	v_mfma_f32_32x32x16_bf16 v[32:47], v[144:147], v[176:179], v[32:47]
	v_add_u32_e32 v14, s95, v242
	ds_read_b64_tr_b16 v[144:145], v14 offset:34816
	ds_read_b64_tr_b16 v[146:147], v14 offset:37376
	ds_read_b64_tr_b16 v[52:53], v14 offset:34880
	ds_read_b64_tr_b16 v[54:55], v14 offset:37440
	ds_read_b64_tr_b16 v[56:57], v14 offset:34944
	ds_read_b64_tr_b16 v[58:59], v14 offset:37504
	ds_read_b64_tr_b16 v[60:61], v14 offset:35008
	ds_read_b64_tr_b16 v[62:63], v14 offset:37568
	ds_read_b64_tr_b16 v[64:65], v14 offset:39936
	ds_read_b64_tr_b16 v[66:67], v14 offset:42496
	v_cvt_pk_bf16_f32 v2, v16, v17
	v_cvt_pk_bf16_f32 v3, v18, v19
	v_cvt_pk_bf16_f32 v4, v20, v21
	v_cvt_pk_bf16_f32 v5, v22, v23
	v_add_f32_e32 v15, v22, v15
	v_add_f32_e32 v15, v23, v15
	s_branch .Lfa_chk
.Lfa_half:
	s_waitcnt lgkmcnt(3)
	v_mfma_f32_32x32x16_bf16 v[16:31], v[48:51], v[148:151], 0
	ds_read_b128 v[52:55], v0 offset:8704
	s_waitcnt lgkmcnt(3)
	v_mfma_f32_32x32x16_bf16 v[16:31], v[10:13], v[152:155], v[16:31]
	ds_read_b128 v[56:59], v0 offset:8736
	s_waitcnt lgkmcnt(3)
	v_mfma_f32_32x32x16_bf16 v[16:31], v[6:9], v[156:159], v[16:31]
	ds_read_b128 v[60:63], v0 offset:8768
	s_waitcnt lgkmcnt(3)
	v_mfma_f32_32x32x16_bf16 v[16:31], v[2:5], v[160:163], v[16:31]
	ds_read_b128 v[64:67], v0 offset:8800
	s_waitcnt lgkmcnt(3)
	v_mfma_f32_32x32x16_bf16 v[32:47], v[52:55], v[148:151], 0
	s_waitcnt lgkmcnt(2)
	v_mfma_f32_32x32x16_bf16 v[32:47], v[56:59], v[152:155], v[32:47]
	v_max3_f32 v0, v16, v17, v18
	v_max3_f32 v0, v0, v19, v20
	v_max3_f32 v0, v0, v21, v22
	v_max3_f32 v0, v0, v23, v24
	v_max3_f32 v0, v0, v25, v26
	v_max3_f32 v0, v0, v27, v28
	s_waitcnt lgkmcnt(1)
	v_mfma_f32_32x32x16_bf16 v[32:47], v[60:63], v[156:159], v[32:47]
	v_max3_f32 v0, v0, v29, v30
	v_max_f32_e32 v0, v0, v31
	v_sub_f32_e32 v10, v16, v233
	v_exp_f32_e32 v16, v10
	v_sub_f32_e32 v10, v17, v233
	v_exp_f32_e32 v17, v10
	s_waitcnt lgkmcnt(0)
	v_mfma_f32_32x32x16_bf16 v[32:47], v[64:67], v[160:163], v[32:47]
	v_add_u32_e32 v14, s95, v242
	ds_read_b64_tr_b16 v[144:145], v14 offset:34816
	ds_read_b64_tr_b16 v[146:147], v14 offset:37376
	ds_read_b64_tr_b16 v[52:53], v14 offset:34880
	ds_read_b64_tr_b16 v[54:55], v14 offset:37440
	ds_read_b64_tr_b16 v[56:57], v14 offset:34944
	ds_read_b64_tr_b16 v[58:59], v14 offset:37504
	ds_read_b64_tr_b16 v[60:61], v14 offset:35008
	ds_read_b64_tr_b16 v[62:63], v14 offset:37568
	ds_read_b64_tr_b16 v[64:65], v14 offset:39936
	ds_read_b64_tr_b16 v[66:67], v14 offset:42496
	v_sub_f32_e32 v10, v18, v233
	v_exp_f32_e32 v18, v10
	v_add_f32_e32 v15, 0, v16
	v_sub_f32_e32 v10, v19, v233
	v_exp_f32_e32 v19, v10
	v_add_f32_e32 v15, v17, v15
	v_sub_f32_e32 v10, v20, v233
	v_exp_f32_e32 v20, v10
	v_add_f32_e32 v15, v18, v15
	v_sub_f32_e32 v10, v21, v233
	v_exp_f32_e32 v21, v10
	v_add_f32_e32 v15, v19, v15
	v_sub_f32_e32 v10, v22, v233
	v_exp_f32_e32 v22, v10
	v_add_f32_e32 v15, v20, v15
	v_sub_f32_e32 v10, v23, v233
	v_exp_f32_e32 v23, v10
	v_add_f32_e32 v15, v21, v15
	v_cvt_pk_bf16_f32 v2, v16, v17
	v_cvt_pk_bf16_f32 v3, v18, v19
	v_cvt_pk_bf16_f32 v4, v20, v21
	v_cvt_pk_bf16_f32 v5, v22, v23
	v_add_f32_e32 v15, v22, v15
	v_add_f32_e32 v15, v23, v15
; DI unsigned pack2(float a, float b) { f2_t v = {a, b}; bf2_t r = __builtin_convertvector(v, bf2_t); return __builtin_bit_cast(unsigned, r); }
; DI float fexp2(float x) { return __builtin_amdgcn_exp2f(x); }
; DI float half_max(float v) { const auto r = __builtin_amdgcn_permlane32_swap(__float_as_uint(v), __float_as_uint(v), false, false); return fmaxf(__uint_as_float(r[0]), __uint_as_float(r[1])); }
; template <int PM> DI void attn_phase(const Params& p, int l, char* smem, int* s_item, int wv, int cidx) {
;     ...
;           float mt = sacc[0][0];
; #pragma unroll
;           for (int e = 1; e < 16; ++e) mt = fmaxf(mt, sacc[0][e]);
; #pragma unroll
;           for (int e = 0; e < 16; ++e) mt = fmaxf(mt, sacc[1][e]);
;           mt = half_max(mt);
;           if (__builtin_amdgcn_ballot_w64(mt > m + 8.f) != 0ull) {
;             const float mnew = fmaxf(m, mt);
;             const float alpha = fexp2(m - mnew);
;             m = mnew;
;             lsum *= alpha;
; #pragma unroll
;             for (int db = 0; db < 4; ++db)
; #pragma unroll
;               for (int e = 0; e < 16; ++e) Oacc[db][e] *= alpha;
;           }
;           float ps = 0.f;
; #pragma unroll
;           for (int kb = 0; kb < 2; ++kb)
; #pragma unroll
;             for (int e = 0; e < 16; ++e) { const float pv = fexp2(sacc[kb][e] - m); sacc[kb][e] = pv; ps += pv; }
;           lsum += ps;
; #pragma unroll
;           for (int kb = 0; kb < 2; ++kb)
; #pragma unroll
;             for (int s2 = 0; s2 < 2; ++s2) {
;               u32x4 t;
;               t[0] = pack2(sacc[kb][8 * s2 + 0], sacc[kb][8 * s2 + 1]);
;               t[1] = pack2(sacc[kb][8 * s2 + 2], sacc[kb][8 * s2 + 3]);
;               t[2] = pack2(sacc[kb][8 * s2 + 4], sacc[kb][8 * s2 + 5]);
;               t[3] = pack2(sacc[kb][8 * s2 + 6], sacc[kb][8 * s2 + 7]);
;               pf[kb][s2] = __builtin_bit_cast(bf16x8, t);
;             }
;           if (!shift) ATT_PV_RUN(vcur); else pend = true;
.Lfa_chk:
	v_max3_f32 v0, v0, v32, v33
	v_max3_f32 v0, v0, v34, v35
	v_max3_f32 v0, v0, v36, v37
	v_max3_f32 v0, v0, v38, v39
	v_max3_f32 v0, v0, v40, v41
	v_max3_f32 v0, v0, v42, v43
	v_max3_f32 v0, v0, v44, v45
	v_max3_f32 v0, v0, v46, v47
	v_mov_b32_e32 v10, v0
	s_nop 1
	v_permlane32_swap_b32_e32 v0, v10
	v_max_f32_e32 v0, v0, v10
	v_add_f32_e32 v10, 0x41000000, v233
	v_cmp_gt_f32_e32 vcc, v0, v10
	s_cbranch_vccnz .Lfa_rare
	s_waitcnt lgkmcnt(8)
	v_mfma_f32_32x32x16_bf16 v[128:143], v[144:147], v[2:5], v[128:143]
	ds_read_b64_tr_b16 v[144:145], v14 offset:40000
	ds_read_b64_tr_b16 v[146:147], v14 offset:42560
	v_sub_f32_e32 v0, v24, v233
	v_exp_f32_e32 v24, v0
	v_sub_f32_e32 v0, v25, v233
	v_exp_f32_e32 v25, v0
	v_sub_f32_e32 v0, v26, v233
	v_exp_f32_e32 v26, v0
	v_add_f32_e32 v15, v24, v15
	s_waitcnt lgkmcnt(8)
	v_mfma_f32_32x32x16_bf16 v[112:127], v[52:55], v[2:5], v[112:127]
	ds_read_b64_tr_b16 v[52:53], v14 offset:40064
	ds_read_b64_tr_b16 v[54:55], v14 offset:42624
	v_sub_f32_e32 v0, v27, v233
	v_exp_f32_e32 v27, v0
	v_add_f32_e32 v15, v25, v15
	v_sub_f32_e32 v0, v28, v233
	v_exp_f32_e32 v28, v0
	v_add_f32_e32 v15, v26, v15
	v_sub_f32_e32 v0, v29, v233
	s_waitcnt lgkmcnt(8)
	v_mfma_f32_32x32x16_bf16 v[96:111], v[56:59], v[2:5], v[96:111]
	ds_read_b64_tr_b16 v[56:57], v14 offset:40128
	ds_read_b64_tr_b16 v[58:59], v14 offset:42688
	v_exp_f32_e32 v29, v0
	v_add_f32_e32 v15, v27, v15
	v_sub_f32_e32 v0, v30, v233
	v_exp_f32_e32 v30, v0
	v_add_f32_e32 v15, v28, v15
	v_sub_f32_e32 v0, v31, v233
	v_exp_f32_e32 v31, v0
	s_waitcnt lgkmcnt(8)
	v_mfma_f32_32x32x16_bf16 v[80:95], v[60:63], v[2:5], v[80:95]
	ds_read_b64_tr_b16 v[60:61], v14 offset:45056
	ds_read_b64_tr_b16 v[62:63], v14 offset:47616
	v_add_f32_e32 v15, v29, v15
	v_cvt_pk_bf16_f32 v6, v24, v25
	v_cvt_pk_bf16_f32 v7, v26, v27
	v_cvt_pk_bf16_f32 v8, v28, v29
	v_cvt_pk_bf16_f32 v9, v30, v31
	v_add_f32_e32 v15, v30, v15
	v_add_f32_e32 v15, v31, v15
	s_waitcnt lgkmcnt(8)
	v_mfma_f32_32x32x16_bf16 v[128:143], v[64:67], v[6:9], v[128:143]
	ds_read_b64_tr_b16 v[64:65], v14 offset:45120
	ds_read_b64_tr_b16 v[66:67], v14 offset:47680
	v_sub_f32_e32 v0, v32, v233
	v_exp_f32_e32 v32, v0
	v_sub_f32_e32 v0, v33, v233
	v_exp_f32_e32 v33, v0
	v_sub_f32_e32 v0, v34, v233
	v_exp_f32_e32 v34, v0
	v_add_f32_e32 v15, v32, v15
	s_waitcnt lgkmcnt(8)
	v_mfma_f32_32x32x16_bf16 v[112:127], v[144:147], v[6:9], v[112:127]
	ds_read_b64_tr_b16 v[144:145], v14 offset:45184
	ds_read_b64_tr_b16 v[146:147], v14 offset:47744
	v_sub_f32_e32 v0, v35, v233
	v_exp_f32_e32 v35, v0
	v_add_f32_e32 v15, v33, v15
	v_sub_f32_e32 v0, v36, v233
	v_exp_f32_e32 v36, v0
	v_add_f32_e32 v15, v34, v15
	v_sub_f32_e32 v0, v37, v233
	s_waitcnt lgkmcnt(8)
	v_mfma_f32_32x32x16_bf16 v[96:111], v[52:55], v[6:9], v[96:111]
	ds_read_b64_tr_b16 v[52:53], v14 offset:45248
	ds_read_b64_tr_b16 v[54:55], v14 offset:47808
	v_exp_f32_e32 v37, v0
	v_add_f32_e32 v15, v35, v15
	v_sub_f32_e32 v0, v38, v233
	v_exp_f32_e32 v38, v0
	v_add_f32_e32 v15, v36, v15
	v_sub_f32_e32 v0, v39, v233
	v_exp_f32_e32 v39, v0
	s_waitcnt lgkmcnt(8)
	v_mfma_f32_32x32x16_bf16 v[80:95], v[56:59], v[6:9], v[80:95]
	ds_read_b64_tr_b16 v[56:57], v14 offset:50176
	ds_read_b64_tr_b16 v[58:59], v14 offset:52736
	v_add_f32_e32 v15, v37, v15
	v_cvt_pk_bf16_f32 v10, v32, v33
	v_cvt_pk_bf16_f32 v11, v34, v35
	v_cvt_pk_bf16_f32 v12, v36, v37
	v_cvt_pk_bf16_f32 v13, v38, v39
	v_add_f32_e32 v15, v38, v15
	v_add_f32_e32 v15, v39, v15
	s_waitcnt lgkmcnt(8)
	v_mfma_f32_32x32x16_bf16 v[128:143], v[60:63], v[10:13], v[128:143]
	ds_read_b64_tr_b16 v[60:61], v14 offset:50240
	ds_read_b64_tr_b16 v[62:63], v14 offset:52800
	v_sub_f32_e32 v0, v40, v233
	v_exp_f32_e32 v40, v0
	v_sub_f32_e32 v0, v41, v233
	v_exp_f32_e32 v41, v0
	v_sub_f32_e32 v0, v42, v233
	v_exp_f32_e32 v42, v0
	v_add_f32_e32 v15, v40, v15
	s_waitcnt lgkmcnt(8)
	v_mfma_f32_32x32x16_bf16 v[112:127], v[64:67], v[10:13], v[112:127]
	ds_read_b64_tr_b16 v[64:65], v14 offset:50304
	ds_read_b64_tr_b16 v[66:67], v14 offset:52864
	v_sub_f32_e32 v0, v43, v233
	v_exp_f32_e32 v43, v0
	v_add_f32_e32 v15, v41, v15
	v_sub_f32_e32 v0, v44, v233
	v_exp_f32_e32 v44, v0
	v_add_f32_e32 v15, v42, v15
	v_sub_f32_e32 v0, v45, v233
	s_waitcnt lgkmcnt(8)
	v_mfma_f32_32x32x16_bf16 v[96:111], v[144:147], v[10:13], v[96:111]
	ds_read_b64_tr_b16 v[144:145], v14 offset:50368
	ds_read_b64_tr_b16 v[146:147], v14 offset:52928
	v_exp_f32_e32 v45, v0
	v_add_f32_e32 v15, v43, v15
	v_sub_f32_e32 v0, v46, v233
	v_exp_f32_e32 v46, v0
	v_add_f32_e32 v15, v44, v15
	v_sub_f32_e32 v0, v47, v233
	v_exp_f32_e32 v47, v0
	s_waitcnt lgkmcnt(8)
	v_mfma_f32_32x32x16_bf16 v[80:95], v[52:55], v[10:13], v[80:95]
	v_add_f32_e32 v15, v45, v15
	v_cvt_pk_bf16_f32 v48, v40, v41
	v_cvt_pk_bf16_f32 v49, v42, v43
	v_cvt_pk_bf16_f32 v50, v44, v45
	v_cvt_pk_bf16_f32 v51, v46, v47
	v_add_f32_e32 v15, v46, v15
	v_add_f32_e32 v15, v47, v15
	s_waitcnt lgkmcnt(6)
	v_mfma_f32_32x32x16_bf16 v[128:143], v[56:59], v[48:51], v[128:143]
	s_waitcnt lgkmcnt(4)
	v_mfma_f32_32x32x16_bf16 v[112:127], v[60:63], v[48:51], v[112:127]
	s_waitcnt lgkmcnt(2)
	v_mfma_f32_32x32x16_bf16 v[96:111], v[64:67], v[48:51], v[96:111]
	s_waitcnt lgkmcnt(0)
	v_mfma_f32_32x32x16_bf16 v[80:95], v[144:147], v[48:51], v[80:95]
	v_add_f32_e32 v235, v235, v15
	s_branch .LBB0_515
; DI float fexp2(float x) { return __builtin_amdgcn_exp2f(x); }
; template <int PM> DI void attn_phase(const Params& p, int l, char* smem, int* s_item, int wv, int cidx) {
;     ...
;           if (__builtin_amdgcn_ballot_w64(mt > m + 8.f) != 0ull) {
;             const float mnew = fmaxf(m, mt);
;             const float alpha = fexp2(m - mnew);
;             m = mnew;
;             lsum *= alpha;
; #pragma unroll
;             for (int db = 0; db < 4; ++db)
; #pragma unroll
;               for (int e = 0; e < 16; ++e) Oacc[db][e] *= alpha;
;           }
.Lfa_rare:
	v_max_f32_e32 v2, v233, v233
	v_max_f32_e32 v2, v2, v0
	v_sub_f32_e32 v0, v233, v2
	v_exp_f32_e32 v0, v0
	v_mov_b32_e32 v233, v2
	v_pk_mul_f32 v[142:143], v[142:143], v[0:1] op_sel_hi:[1,0]
	v_pk_mul_f32 v[140:141], v[140:141], v[0:1] op_sel_hi:[1,0]
	v_pk_mul_f32 v[138:139], v[138:139], v[0:1] op_sel_hi:[1,0]
	v_pk_mul_f32 v[136:137], v[136:137], v[0:1] op_sel_hi:[1,0]
	v_pk_mul_f32 v[134:135], v[134:135], v[0:1] op_sel_hi:[1,0]
	v_pk_mul_f32 v[132:133], v[132:133], v[0:1] op_sel_hi:[1,0]
	v_pk_mul_f32 v[130:131], v[130:131], v[0:1] op_sel_hi:[1,0]
	v_pk_mul_f32 v[128:129], v[128:129], v[0:1] op_sel_hi:[1,0]
	v_pk_mul_f32 v[126:127], v[126:127], v[0:1] op_sel_hi:[1,0]
	v_pk_mul_f32 v[124:125], v[124:125], v[0:1] op_sel_hi:[1,0]
	v_pk_mul_f32 v[122:123], v[122:123], v[0:1] op_sel_hi:[1,0]
	v_pk_mul_f32 v[120:121], v[120:121], v[0:1] op_sel_hi:[1,0]
	v_pk_mul_f32 v[118:119], v[118:119], v[0:1] op_sel_hi:[1,0]
	v_pk_mul_f32 v[116:117], v[116:117], v[0:1] op_sel_hi:[1,0]
	v_pk_mul_f32 v[114:115], v[114:115], v[0:1] op_sel_hi:[1,0]
	v_pk_mul_f32 v[112:113], v[112:113], v[0:1] op_sel_hi:[1,0]
	v_pk_mul_f32 v[110:111], v[110:111], v[0:1] op_sel_hi:[1,0]
	v_pk_mul_f32 v[108:109], v[108:109], v[0:1] op_sel_hi:[1,0]
	v_pk_mul_f32 v[106:107], v[106:107], v[0:1] op_sel_hi:[1,0]
	v_pk_mul_f32 v[104:105], v[104:105], v[0:1] op_sel_hi:[1,0]
	v_pk_mul_f32 v[102:103], v[102:103], v[0:1] op_sel_hi:[1,0]
	v_pk_mul_f32 v[100:101], v[100:101], v[0:1] op_sel_hi:[1,0]
	v_pk_mul_f32 v[98:99], v[98:99], v[0:1] op_sel_hi:[1,0]
	v_pk_mul_f32 v[96:97], v[96:97], v[0:1] op_sel_hi:[1,0]
	v_pk_mul_f32 v[94:95], v[94:95], v[0:1] op_sel_hi:[1,0]
	v_pk_mul_f32 v[92:93], v[92:93], v[0:1] op_sel_hi:[1,0]
	v_pk_mul_f32 v[90:91], v[90:91], v[0:1] op_sel_hi:[1,0]
	v_pk_mul_f32 v[88:89], v[88:89], v[0:1] op_sel_hi:[1,0]
	v_pk_mul_f32 v[86:87], v[86:87], v[0:1] op_sel_hi:[1,0]
	v_pk_mul_f32 v[84:85], v[84:85], v[0:1] op_sel_hi:[1,0]
	v_pk_mul_f32 v[82:83], v[82:83], v[0:1] op_sel_hi:[1,0]
	v_pk_mul_f32 v[80:81], v[80:81], v[0:1] op_sel_hi:[1,0]
	v_mul_f32_e32 v235, v235, v0
	s_mov_b32 s32, 1
	s_waitcnt lgkmcnt(0)
	s_branch .Lfa_redo
